# GDN look-ahead pairing: even groups compute next group's K/Q.S products in idle MFMA rows, odd groups correct with one MFMA via cross-Gram staged in LDS; packed LDS reads
# speedup vs baseline: 1.2489x; 1.1396x over previous
.LBB0_547:
	s_or_b64 exec, exec, s[4:5]
	v_and_b32_e32 v165, 63, v180
	v_lshrrev_b32_e32 v168, 6, v180
	v_mul_u32_u24_e32 v163, 0x1080, v168
	v_lshlrev_b32_e32 v164, 7, v168
	v_lshrrev_b32_e32 v168, 1, v165
	v_lshl_add_u32 v164, v168, 2, v164
	v_add_u32_e32 v164, 0x15800, v164
	v_and_b32_e32 v165, 1, v165
	v_lshl_add_u32 v163, v165, 8, v163
	v_bfe_u32 v165, v168, 2, 2
	v_add_u32_e32 v165, 4, v165
	v_mul_u32_u24_e32 v165, 0x210, v165
	v_add_u32_e32 v162, v163, v165
	v_bfe_u32 v165, v168, 4, 1
	v_sub_u32_e32 v165, 1, v165
	v_mul_u32_u24_e32 v165, 0x8400, v165
	v_add_u32_e32 v162, v162, v165
	v_and_b32_e32 v165, 3, v168
	v_mul_u32_u24_e32 v165, 0x210, v165
	v_add_u32_e32 v163, v163, v165
	v_add_u32_e32 v163, 0x8400, v163
	v_mov_b32_e32 v166, 0
	v_mov_b32_e32 v167, 0
	ds_read_b128 v[216:219], v162 offset:0
	ds_read_b128 v[220:223], v162 offset:16
	ds_read_b128 v[224:227], v163 offset:0
	ds_read_b128 v[228:231], v163 offset:16
	ds_read_b128 v[232:235], v162 offset:32
	ds_read_b128 v[236:239], v162 offset:48
	ds_read_b128 v[170:173], v163 offset:32
	ds_read_b128 v[174:177], v163 offset:48
	s_waitcnt lgkmcnt(4)
	v_pk_fma_f32 v[166:167], v[216:217], v[224:225], v[166:167]
	v_pk_fma_f32 v[166:167], v[218:219], v[226:227], v[166:167]
	v_pk_fma_f32 v[166:167], v[220:221], v[228:229], v[166:167]
	v_pk_fma_f32 v[166:167], v[222:223], v[230:231], v[166:167]
	ds_read_b128 v[216:219], v162 offset:64
	ds_read_b128 v[220:223], v162 offset:80
	ds_read_b128 v[224:227], v163 offset:64
	ds_read_b128 v[228:231], v163 offset:80
	s_waitcnt lgkmcnt(4)
	v_pk_fma_f32 v[166:167], v[232:233], v[170:171], v[166:167]
	v_pk_fma_f32 v[166:167], v[234:235], v[172:173], v[166:167]
	v_pk_fma_f32 v[166:167], v[236:237], v[174:175], v[166:167]
	v_pk_fma_f32 v[166:167], v[238:239], v[176:177], v[166:167]
	ds_read_b128 v[232:235], v162 offset:96
	ds_read_b128 v[236:239], v162 offset:112
	ds_read_b128 v[170:173], v163 offset:96
	ds_read_b128 v[174:177], v163 offset:112
	s_waitcnt lgkmcnt(4)
	v_pk_fma_f32 v[166:167], v[216:217], v[224:225], v[166:167]
	v_pk_fma_f32 v[166:167], v[218:219], v[226:227], v[166:167]
	v_pk_fma_f32 v[166:167], v[220:221], v[228:229], v[166:167]
	v_pk_fma_f32 v[166:167], v[222:223], v[230:231], v[166:167]
	ds_read_b128 v[216:219], v162 offset:128
	ds_read_b128 v[220:223], v162 offset:144
	ds_read_b128 v[224:227], v163 offset:128
	ds_read_b128 v[228:231], v163 offset:144
	s_waitcnt lgkmcnt(4)
	v_pk_fma_f32 v[166:167], v[232:233], v[170:171], v[166:167]
	v_pk_fma_f32 v[166:167], v[234:235], v[172:173], v[166:167]
	v_pk_fma_f32 v[166:167], v[236:237], v[174:175], v[166:167]
	v_pk_fma_f32 v[166:167], v[238:239], v[176:177], v[166:167]
	ds_read_b128 v[232:235], v162 offset:160
	ds_read_b128 v[236:239], v162 offset:176
	ds_read_b128 v[170:173], v163 offset:160
	ds_read_b128 v[174:177], v163 offset:176
	s_waitcnt lgkmcnt(4)
	v_pk_fma_f32 v[166:167], v[216:217], v[224:225], v[166:167]
	v_pk_fma_f32 v[166:167], v[218:219], v[226:227], v[166:167]
	v_pk_fma_f32 v[166:167], v[220:221], v[228:229], v[166:167]
	v_pk_fma_f32 v[166:167], v[222:223], v[230:231], v[166:167]
	ds_read_b128 v[216:219], v162 offset:192
	ds_read_b128 v[220:223], v162 offset:208
	ds_read_b128 v[224:227], v163 offset:192
	ds_read_b128 v[228:231], v163 offset:208
	s_waitcnt lgkmcnt(4)
	v_pk_fma_f32 v[166:167], v[232:233], v[170:171], v[166:167]
	v_pk_fma_f32 v[166:167], v[234:235], v[172:173], v[166:167]
	v_pk_fma_f32 v[166:167], v[236:237], v[174:175], v[166:167]
	v_pk_fma_f32 v[166:167], v[238:239], v[176:177], v[166:167]
	ds_read_b128 v[232:235], v162 offset:224
	ds_read_b128 v[236:239], v162 offset:240
	ds_read_b128 v[170:173], v163 offset:224
	ds_read_b128 v[174:177], v163 offset:240
	s_waitcnt lgkmcnt(4)
	v_pk_fma_f32 v[166:167], v[216:217], v[224:225], v[166:167]
	v_pk_fma_f32 v[166:167], v[218:219], v[226:227], v[166:167]
	v_pk_fma_f32 v[166:167], v[220:221], v[228:229], v[166:167]
	v_pk_fma_f32 v[166:167], v[222:223], v[230:231], v[166:167]
	s_waitcnt lgkmcnt(0)
	v_pk_fma_f32 v[166:167], v[232:233], v[170:171], v[166:167]
	v_pk_fma_f32 v[166:167], v[234:235], v[172:173], v[166:167]
	v_pk_fma_f32 v[166:167], v[236:237], v[174:175], v[166:167]
	v_pk_fma_f32 v[166:167], v[238:239], v[176:177], v[166:167]
	v_add_f32_e32 v166, v166, v167
	s_nop 1
	v_add_f32_dpp v166, v166, v166 quad_perm:[1,0,3,2] row_mask:0xf bank_mask:0xf bound_ctrl:1
	ds_write_b32 v164, v166
	s_lshl_b32 s0, s17, 6
	s_add_i32 s72, s0, s16
	v_and_b32_e32 v128, 63, v112
	s_cmp_eq_u32 s17, 31
	s_waitcnt lgkmcnt(0)
	s_barrier
	s_cbranch_scc1 .LBB0_549
	s_add_i32 s0, s72, 64
	s_mov_b32 s1, s73
	v_ashrrev_i32_e32 v27, 31, v26
	v_lshlrev_b32_e32 v2, 1, v23
	v_mov_b32_e32 v3, v94
	v_ashrrev_i32_e32 v23, 31, v22
	v_ashrrev_i32_e32 v25, 31, v24
	v_lshl_add_u64 v[18:19], s[0:1], 0, v[26:27]
	v_mov_b64_e32 v[20:21], s[12:13]
	v_lshl_add_u64 v[10:11], s[8:9], 0, v[2:3]
	v_lshl_add_u64 v[2:3], s[0:1], 0, v[22:23]
	v_lshl_add_u64 v[12:13], s[0:1], 0, v[24:25]
	v_mad_u64_u32 v[20:21], s[4:5], v18, s83, v[20:21]
	v_mad_u64_u32 v[6:7], s[4:5], v2, s83, v[10:11]
	v_mad_u64_u32 v[14:15], s[4:5], v12, s83, v[10:11]
	v_mad_i32_i24 v21, v19, s83, v21
	v_lshlrev_b32_e32 v18, 1, v28
	v_mov_b32_e32 v19, v94
	v_mad_i32_i24 v7, v3, s83, v7
	v_mad_i32_i24 v15, v13, s83, v15
	v_lshl_add_u64 v[18:19], v[20:21], 0, v[18:19]
	v_or_b32_e32 v22, s0, v128
	v_mov_b64_e32 v[20:21], s[14:15]
	global_load_dwordx4 v[2:5], v[6:7], off
	s_nop 0
	global_load_dwordx4 v[6:9], v[6:7], off offset:1024
	s_nop 0
	global_load_dwordx4 v[10:13], v[14:15], off
	s_nop 0
	global_load_dwordx4 v[14:17], v[14:15], off offset:1024
	v_mad_u64_u32 v[22:23], s[0:1], v22, s87, v[20:21]
	global_load_dwordx4 v[18:21], v[18:19], off offset:2048
	s_nop 0
	global_load_dword v126, v[22:23], off offset:512
	global_load_dword v127, v[22:23], off offset:528
.LBB0_549:
	v_readfirstlane_b32 s0, v180
	s_nop 1
	s_cmpk_ge_u32 s0, 0x100
	s_cbranch_scc1 .Lgdn_done
	v_and_b32_e32 v166, 15, v180
	v_bfe_u32 v167, v180, 4, 2
	v_lshrrev_b32_e32 v168, 6, v180
	v_and_b32_e32 v177, 3, v166
	v_bfe_u32 v178, v166, 3, 1
	v_lshl_add_u32 v177, v178, 2, v177
	v_mul_u32_u24_e32 v177, 0x210, v177
	v_and_b32_e32 v87, 7, v166
	v_lshlrev_b32_e32 v87, 4, v87
	v_lshl_add_u32 v87, v167, 2, v87
	v_add_u32_e32 v87, 0x15800, v87
	v_and_b32_e32 v178, 4, v166
	v_sub_u32_e32 v178, 4, v178
	v_mul_u32_u24_e32 v178, 0x2100, v178
	v_lshl_add_u32 v169, v167, 4, v177
	v_add_u32_e32 v169, v169, v178
	v_mul_u32_u24_e32 v177, 0x210, v167
	v_lshl_add_u32 v170, v166, 2, v177
	v_add_u32_e32 v170, 0x8400, v170
	v_add_u32_e32 v237, 0x840, v170
	v_add_u32_e32 v95, 0x1080, v170
	v_lshlrev_b32_e32 v177, 6, v168
	v_lshl_add_u32 v177, v166, 2, v177
	v_add_u32_e32 v171, 0x10800, v177
	v_lshl_add_u32 v172, v167, 8, v177
	v_add_u32_e32 v172, 0x1d800, v172
	v_mov_b32_e32 v173, 0x14800
	v_lshlrev_b32_e32 v174, 5, v167
	v_add_u32_e32 v174, 0x14900, v174
	v_mov_b32_e32 v175, 0x21900
	v_lshl_add_u32 v176, v167, 2, v175
	v_cmp_eq_u32_e32 vcc, 1, v167
	v_cmp_eq_u32_e64 s[4:5], 2, v167
	v_cmp_eq_u32_e64 s[6:7], 3, v167
	ds_read_b128 v[22:25], v169 offset:0
	ds_read_b128 v[26:29], v169 offset:64
	ds_read_b128 v[30:33], v169 offset:128
	ds_read_b128 v[34:37], v169 offset:192
	ds_read_b128 v[38:41], v169 offset:256
	ds_read_b128 v[42:45], v169 offset:320
	ds_read_b128 v[46:49], v169 offset:384
	ds_read_b128 v[50:53], v169 offset:448
	ds_read2_b32 v[54:55], v170 offset0:0 offset1:16
	ds_read2_b32 v[56:57], v170 offset0:32 offset1:48
	ds_read2_b32 v[58:59], v170 offset0:64 offset1:80
	ds_read2_b32 v[60:61], v170 offset0:96 offset1:112
	ds_read2st64_b32 v[70:71], v171 offset0:0 offset1:1
	ds_read2st64_b32 v[72:73], v171 offset0:2 offset1:3
	ds_read_b128 v[132:135], v175 offset:0
	ds_read_b128 v[136:139], v175 offset:256
	ds_read_b32 v151, v176 offset:256
	ds_read_b32 v152, v176 offset:512
	ds_read_b32 v150, v173 offset:32
	ds_read_b64 v[148:149], v173 offset:64
	ds_read_b128 v[140:143], v173 offset:96
	ds_read_b128 v[144:147], v174 offset:0
	s_mov_b32 s1, 0
	s_waitcnt lgkmcnt(0)
.Lgdn_loop:
	s_waitcnt lgkmcnt(1)
	v_mfma_f32_16x16x4_f32 v[96:99], v22, v184, 0
	v_mfma_f32_16x16x4_f32 v[100:103], v23, v185, 0
	v_mfma_f32_16x16x4_f32 v[96:99], v24, v186, v[96:99]
	v_mfma_f32_16x16x4_f32 v[100:103], v25, v187, v[100:103]
	v_pk_mul_f32 v[184:185], v[184:185], v[138:139] op_sel:[0,1] op_sel_hi:[1,1]
	v_pk_mul_f32 v[186:187], v[186:187], v[138:139] op_sel:[0,1] op_sel_hi:[1,1]
	v_mul_f32_e32 v129, v132, v70
	v_mul_f32_e32 v130, v133, v71
	v_mul_f32_e32 v131, v134, v72
	v_mfma_f32_16x16x4_f32 v[96:99], v26, v188, v[96:99]
	v_mfma_f32_16x16x4_f32 v[100:103], v27, v189, v[100:103]
	v_mfma_f32_16x16x4_f32 v[96:99], v28, v190, v[96:99]
	v_mfma_f32_16x16x4_f32 v[100:103], v29, v191, v[100:103]
	v_pk_mul_f32 v[188:189], v[188:189], v[138:139] op_sel:[0,1] op_sel_hi:[1,1]
	v_pk_mul_f32 v[190:191], v[190:191], v[138:139] op_sel:[0,1] op_sel_hi:[1,1]
	v_mul_f32_e32 v153, v135, v73
	v_mul_f32_e64 v114, -v132, v136
	v_mul_f32_e64 v115, -v133, v137
	v_mfma_f32_16x16x4_f32 v[96:99], v30, v192, v[96:99]
	v_mfma_f32_16x16x4_f32 v[100:103], v31, v193, v[100:103]
	v_mfma_f32_16x16x4_f32 v[96:99], v32, v194, v[96:99]
	v_mfma_f32_16x16x4_f32 v[100:103], v33, v195, v[100:103]
	v_pk_mul_f32 v[192:193], v[192:193], v[138:139] op_sel:[0,1] op_sel_hi:[1,1]
	v_pk_mul_f32 v[194:195], v[194:195], v[138:139] op_sel:[0,1] op_sel_hi:[1,1]
	v_mul_f32_e64 v116, -v134, v138
	v_mul_f32_e64 v117, -v135, v139
	ds_read_b32 v86, v87 offset:0
	v_mfma_f32_16x16x4_f32 v[96:99], v34, v196, v[96:99]
	v_mfma_f32_16x16x4_f32 v[100:103], v35, v197, v[100:103]
	v_mfma_f32_16x16x4_f32 v[96:99], v36, v198, v[96:99]
	v_mfma_f32_16x16x4_f32 v[100:103], v37, v199, v[100:103]
	v_pk_mul_f32 v[196:197], v[196:197], v[138:139] op_sel:[0,1] op_sel_hi:[1,1]
	v_pk_mul_f32 v[198:199], v[198:199], v[138:139] op_sel:[0,1] op_sel_hi:[1,1]
	ds_read2_b32 v[62:63], v237 offset0:0 offset1:16
	ds_read2_b32 v[64:65], v237 offset0:32 offset1:48
	ds_read2_b32 v[66:67], v237 offset0:64 offset1:80
	v_mfma_f32_16x16x4_f32 v[96:99], v38, v200, v[96:99]
	v_mfma_f32_16x16x4_f32 v[100:103], v39, v201, v[100:103]
	v_mfma_f32_16x16x4_f32 v[96:99], v40, v202, v[96:99]
	v_mfma_f32_16x16x4_f32 v[100:103], v41, v203, v[100:103]
	v_pk_mul_f32 v[200:201], v[200:201], v[138:139] op_sel:[0,1] op_sel_hi:[1,1]
	v_pk_mul_f32 v[202:203], v[202:203], v[138:139] op_sel:[0,1] op_sel_hi:[1,1]
	ds_read2_b32 v[68:69], v237 offset0:96 offset1:112
	ds_read2st64_b32 v[74:75], v171 offset0:4 offset1:5
	ds_read2st64_b32 v[76:77], v171 offset0:6 offset1:7
	v_mfma_f32_16x16x4_f32 v[96:99], v42, v204, v[96:99]
	v_mfma_f32_16x16x4_f32 v[100:103], v43, v205, v[100:103]
	v_mfma_f32_16x16x4_f32 v[96:99], v44, v206, v[96:99]
	v_mfma_f32_16x16x4_f32 v[100:103], v45, v207, v[100:103]
	v_pk_mul_f32 v[204:205], v[204:205], v[138:139] op_sel:[0,1] op_sel_hi:[1,1]
	v_pk_mul_f32 v[206:207], v[206:207], v[138:139] op_sel:[0,1] op_sel_hi:[1,1]
	ds_read_b128 v[216:219], v175 offset:16
	ds_read_b128 v[220:223], v175 offset:272
	ds_read_b32 v235, v176 offset:272
	v_mfma_f32_16x16x4_f32 v[96:99], v46, v208, v[96:99]
	v_mfma_f32_16x16x4_f32 v[100:103], v47, v209, v[100:103]
	v_mfma_f32_16x16x4_f32 v[96:99], v48, v210, v[96:99]
	v_mfma_f32_16x16x4_f32 v[100:103], v49, v211, v[100:103]
	v_pk_mul_f32 v[208:209], v[208:209], v[138:139] op_sel:[0,1] op_sel_hi:[1,1]
	v_pk_mul_f32 v[210:211], v[210:211], v[138:139] op_sel:[0,1] op_sel_hi:[1,1]
	ds_read_b32 v236, v176 offset:528
	ds_read_b32 v234, v173 offset:176
	ds_read_b64 v[232:233], v173 offset:208
	v_mfma_f32_16x16x4_f32 v[96:99], v50, v212, v[96:99]
	v_mfma_f32_16x16x4_f32 v[100:103], v51, v213, v[100:103]
	v_mfma_f32_16x16x4_f32 v[96:99], v52, v214, v[96:99]
	v_mfma_f32_16x16x4_f32 v[100:103], v53, v215, v[100:103]
	v_pk_mul_f32 v[212:213], v[212:213], v[138:139] op_sel:[0,1] op_sel_hi:[1,1]
	v_pk_mul_f32 v[214:215], v[214:215], v[138:139] op_sel:[0,1] op_sel_hi:[1,1]
	ds_read_b128 v[224:227], v173 offset:240
	ds_read_b128 v[228:231], v174 offset:144
	s_nop 7
	s_nop 1
	v_pk_add_f32 v[78:79], v[96:97], v[100:101]
	v_pk_add_f32 v[80:81], v[98:99], v[102:103]
	v_pk_add_f32 v[96:97], v[96:97], v[100:101]
	v_pk_add_f32 v[98:99], v[98:99], v[102:103]
	s_nop 0
	v_permlane32_swap_b32_e32 v96, v78
	v_permlane32_swap_b32_e32 v97, v79
	v_permlane32_swap_b32_e32 v98, v80
	v_permlane32_swap_b32_e32 v99, v81
	v_mov_b32_e32 v82, v96
	v_mov_b32_e32 v83, v97
	v_mov_b32_e32 v84, v98
	v_mov_b32_e32 v85, v99
	s_nop 0
	v_permlane16_swap_b32_e32 v96, v82
	v_permlane16_swap_b32_e32 v97, v83
	v_permlane16_swap_b32_e32 v98, v84
	v_permlane16_swap_b32_e32 v99, v85
	v_fma_f32 v108, v114, v96, v129
	v_fma_f32 v109, v115, v97, v130
	v_fma_f32 v110, v116, v98, v131
	v_fma_f32 v111, v117, v99, v153
	v_fma_f32 v109, -v150, v108, v109
	v_fma_f32 v110, -v148, v108, v110
	v_fma_f32 v111, -v140, v108, v111
	v_fma_f32 v110, -v149, v109, v110
	v_fma_f32 v111, -v141, v109, v111
	v_fma_f32 v111, -v142, v110, v111
	v_cndmask_b32_e32 v182, v108, v109, vcc
	v_cndmask_b32_e64 v182, v182, v110, s[4:5]
	v_cndmask_b32_e64 v182, v182, v111, s[6:7]
	v_mul_f32_e32 v182, v152, v182
	s_nop 1
	v_mfma_f32_16x16x4_f32 v[184:187], v54, v182, v[184:187]
	v_mfma_f32_16x16x4_f32 v[188:191], v55, v182, v[188:191]
	v_mfma_f32_16x16x4_f32 v[192:195], v56, v182, v[192:195]
	v_mfma_f32_16x16x4_f32 v[196:199], v57, v182, v[196:199]
	v_mfma_f32_16x16x4_f32 v[200:203], v58, v182, v[200:203]
	v_mfma_f32_16x16x4_f32 v[204:207], v59, v182, v[204:207]
	v_mfma_f32_16x16x4_f32 v[208:211], v60, v182, v[208:211]
	v_mfma_f32_16x16x4_f32 v[212:215], v61, v182, v[212:215]
	v_pk_mul_f32 v[78:79], v[78:79], v[138:139] op_sel:[0,1] op_sel_hi:[1,1]
	v_pk_mul_f32 v[80:81], v[80:81], v[138:139] op_sel:[0,1] op_sel_hi:[1,1]
	v_cndmask_b32_e32 v183, v82, v83, vcc
	v_cndmask_b32_e64 v183, v183, v84, s[4:5]
	v_cndmask_b32_e64 v183, v183, v85, s[6:7]
	v_mul_f32_e32 v179, v151, v183
	v_fmac_f32_e32 v179, v144, v108
	v_fmac_f32_e32 v179, v145, v109
	v_fmac_f32_e32 v179, v146, v110
	v_fmac_f32_e32 v179, v147, v111
	ds_write_b32 v172, v179 offset:0
	s_waitcnt lgkmcnt(1)
	v_mfma_f32_16x16x4_f32 v[96:99], v86, v182, v[78:81]
	v_pk_mul_f32 v[184:185], v[184:185], v[222:223] op_sel:[0,1] op_sel_hi:[1,1]
	v_pk_mul_f32 v[186:187], v[186:187], v[222:223] op_sel:[0,1] op_sel_hi:[1,1]
	v_pk_mul_f32 v[188:189], v[188:189], v[222:223] op_sel:[0,1] op_sel_hi:[1,1]
	v_pk_mul_f32 v[190:191], v[190:191], v[222:223] op_sel:[0,1] op_sel_hi:[1,1]
	v_pk_mul_f32 v[192:193], v[192:193], v[222:223] op_sel:[0,1] op_sel_hi:[1,1]
	v_pk_mul_f32 v[194:195], v[194:195], v[222:223] op_sel:[0,1] op_sel_hi:[1,1]
	v_pk_mul_f32 v[196:197], v[196:197], v[222:223] op_sel:[0,1] op_sel_hi:[1,1]
	v_pk_mul_f32 v[198:199], v[198:199], v[222:223] op_sel:[0,1] op_sel_hi:[1,1]
	v_pk_mul_f32 v[200:201], v[200:201], v[222:223] op_sel:[0,1] op_sel_hi:[1,1]
	v_pk_mul_f32 v[202:203], v[202:203], v[222:223] op_sel:[0,1] op_sel_hi:[1,1]
	v_pk_mul_f32 v[204:205], v[204:205], v[222:223] op_sel:[0,1] op_sel_hi:[1,1]
	v_pk_mul_f32 v[206:207], v[206:207], v[222:223] op_sel:[0,1] op_sel_hi:[1,1]
	v_pk_mul_f32 v[208:209], v[208:209], v[222:223] op_sel:[0,1] op_sel_hi:[1,1]
	v_pk_mul_f32 v[210:211], v[210:211], v[222:223] op_sel:[0,1] op_sel_hi:[1,1]
	v_pk_mul_f32 v[212:213], v[212:213], v[222:223] op_sel:[0,1] op_sel_hi:[1,1]
	v_pk_mul_f32 v[214:215], v[214:215], v[222:223] op_sel:[0,1] op_sel_hi:[1,1]
	v_mul_f32_e32 v129, v216, v74
	v_mul_f32_e32 v130, v217, v75
	v_mul_f32_e32 v131, v218, v76
	v_mul_f32_e32 v153, v219, v77
	v_mul_f32_e64 v114, -v216, v220
	v_mul_f32_e64 v115, -v217, v221
	v_mul_f32_e64 v116, -v218, v222
	v_mul_f32_e64 v117, -v219, v223
	ds_read_b128 v[22:25], v169 offset:4224
	ds_read_b128 v[26:29], v169 offset:4288
	ds_read_b128 v[30:33], v169 offset:4352
	ds_read_b128 v[34:37], v169 offset:4416
	ds_read_b128 v[38:41], v169 offset:4480
	ds_read_b128 v[42:45], v169 offset:4544
	ds_read_b128 v[46:49], v169 offset:4608
	ds_read_b128 v[50:53], v169 offset:4672
	ds_read2_b32 v[54:55], v95 offset0:0 offset1:16
	ds_read2_b32 v[56:57], v95 offset0:32 offset1:48
	ds_read2_b32 v[58:59], v95 offset0:64 offset1:80
	ds_read2_b32 v[60:61], v95 offset0:96 offset1:112
	ds_read2st64_b32 v[70:71], v171 offset0:8 offset1:9
	ds_read2st64_b32 v[72:73], v171 offset0:10 offset1:11
	ds_read_b128 v[132:135], v175 offset:32
	ds_read_b128 v[136:139], v175 offset:288
	ds_read_b32 v151, v176 offset:288
	ds_read_b32 v152, v176 offset:544
	ds_read_b32 v150, v173 offset:544
	ds_read_b64 v[148:149], v173 offset:576
	ds_read_b128 v[140:143], v173 offset:608
	ds_read_b128 v[144:147], v174 offset:512
	v_mov_b32_e32 v82, v96
	v_mov_b32_e32 v83, v97
	v_mov_b32_e32 v84, v98
	v_mov_b32_e32 v85, v99
	s_nop 0
	v_permlane16_swap_b32_e32 v96, v82
	v_permlane16_swap_b32_e32 v97, v83
	v_permlane16_swap_b32_e32 v98, v84
	v_permlane16_swap_b32_e32 v99, v85
	v_fma_f32 v108, v114, v96, v129
	v_fma_f32 v109, v115, v97, v130
	v_fma_f32 v110, v116, v98, v131
	v_fma_f32 v111, v117, v99, v153
	v_fma_f32 v109, -v234, v108, v109
	v_fma_f32 v110, -v232, v108, v110
	v_fma_f32 v111, -v224, v108, v111
	v_fma_f32 v110, -v233, v109, v110
	v_fma_f32 v111, -v225, v109, v111
	v_fma_f32 v111, -v226, v110, v111
	v_cndmask_b32_e32 v182, v108, v109, vcc
	v_cndmask_b32_e64 v182, v182, v110, s[4:5]
	v_cndmask_b32_e64 v182, v182, v111, s[6:7]
	v_mul_f32_e32 v182, v236, v182
	s_nop 1
	v_mfma_f32_16x16x4_f32 v[184:187], v62, v182, v[184:187]
	v_mfma_f32_16x16x4_f32 v[188:191], v63, v182, v[188:191]
	v_mfma_f32_16x16x4_f32 v[192:195], v64, v182, v[192:195]
	v_mfma_f32_16x16x4_f32 v[196:199], v65, v182, v[196:199]
	v_mfma_f32_16x16x4_f32 v[200:203], v66, v182, v[200:203]
	v_mfma_f32_16x16x4_f32 v[204:207], v67, v182, v[204:207]
	v_mfma_f32_16x16x4_f32 v[208:211], v68, v182, v[208:211]
	v_mfma_f32_16x16x4_f32 v[212:215], v69, v182, v[212:215]
	v_cndmask_b32_e32 v183, v82, v83, vcc
	v_cndmask_b32_e64 v183, v183, v84, s[4:5]
	v_cndmask_b32_e64 v183, v183, v85, s[6:7]
	v_mul_f32_e32 v179, v235, v183
	v_fmac_f32_e32 v179, v228, v108
	v_fmac_f32_e32 v179, v229, v109
	v_fmac_f32_e32 v179, v230, v110
	v_fmac_f32_e32 v179, v231, v111
	ds_write_b32 v172, v179 offset:1024
	v_add_u32_e32 v87, 0x80, v87
	v_add_u32_e32 v169, 0x1080, v169
	v_add_u32_e32 v170, 0x1080, v170
	v_add_u32_e32 v237, 0x1080, v237
	v_add_u32_e32 v95, 0x1080, v95
	v_add_u32_e32 v171, 0x800, v171
	v_add_u32_e32 v172, 0x800, v172
	v_add_u32_e32 v173, 0x200, v173
	v_add_u32_e32 v174, 0x200, v174
	v_add_u32_e32 v175, 0x20, v175
	v_add_u32_e32 v176, 0x20, v176
	s_add_i32 s1, s1, 1
	s_cmp_lg_u32 s1, 8
	s_cbranch_scc1 .Lgdn_loop
